# attention main loops: issue each step's K/V LDS-DMA prefetch at the start of the step (before QK MFMAs)
# speedup vs baseline: 1.0043x; 1.0010x over previous
.LBB0_644:
	v_add_u32_e32 v181, s44, v203
	v_lshl_add_u64 v[186:187], v[184:185], 0, s[42:43]
	v_lshl_add_u64 v[110:111], v[186:187], 0, s[76:77]
	s_add_i32 s44, s70, s35
	s_mov_b32 m0, s44
	s_nop 0
	global_load_lds_dwordx4 v[110:111], off
	v_lshl_add_u64 v[188:189], v[182:183], 0, s[42:43]
	s_mov_b64 s[44:45], 0x15204000
	v_lshl_add_u64 v[110:111], v[188:189], 0, s[44:45]
	s_add_i32 s44, s68, s49
	s_mov_b32 m0, s44
	s_nop 0
	global_load_lds_dwordx4 v[110:111], off
	ds_read_b64_tr_b16 v[176:177], v181 offset:24576
	ds_read_b64_tr_b16 v[178:179], v181 offset:25088
	v_mfma_f32_32x32x16_bf16 v[96:111], v[172:175], v[140:143], v[32:47]
	v_add_f32_e32 v80, v64, v65
	v_add_f32_e32 v80, v66, v80
	v_add_f32_e32 v80, v67, v80
	v_add_f32_e32 v80, v68, v80
	v_add_f32_e32 v80, v69, v80
	v_cvt_pk_bf16_f32 v136, v64, v65
	v_cvt_pk_bf16_f32 v137, v66, v67
	ds_read_b64_tr_b16 v[172:173], v181 offset:28672
	ds_read_b64_tr_b16 v[174:175], v181 offset:29184
	v_add_f32_e32 v64, v70, v80
	v_mfma_f32_32x32x16_bf16 v[80:95], v[168:171], v[140:143], v[32:47]
	v_add_f32_e32 v64, v71, v64
	v_add_f32_e32 v64, v72, v64
	v_add_f32_e32 v116, v73, v64
	v_cvt_pk_bf16_f32 v138, v68, v69
	v_cvt_pk_bf16_f32 v139, v70, v71
	ds_read_b64_tr_b16 v[64:65], v181 offset:25600
	ds_read_b64_tr_b16 v[66:67], v181 offset:26112
	v_mfma_f32_32x32x16_bf16 v[96:111], v[164:167], v[132:135], v[96:111]
	v_add_f32_e32 v68, v74, v116
	v_add_f32_e32 v68, v75, v68
	v_add_f32_e32 v68, v76, v68
	v_add_f32_e32 v116, v77, v68
	v_cvt_pk_bf16_f32 v128, v72, v73
	v_cvt_pk_bf16_f32 v129, v74, v75
	ds_read_b64_tr_b16 v[68:69], v181 offset:29696
	ds_read_b64_tr_b16 v[70:71], v181 offset:30208
	v_mfma_f32_32x32x16_bf16 v[80:95], v[160:163], v[132:135], v[80:95]
	v_add_f32_e32 v72, v78, v116
	v_add_f32_e32 v72, v79, v72
	v_add_f32_e32 v72, v48, v72
	v_add_f32_e32 v116, v49, v72
	v_cvt_pk_bf16_f32 v130, v76, v77
	v_cvt_pk_bf16_f32 v131, v78, v79
	ds_read_b64_tr_b16 v[72:73], v181 offset:26624
	ds_read_b64_tr_b16 v[74:75], v181 offset:27136
	v_mfma_f32_32x32x16_bf16 v[96:111], v[156:159], v[120:123], v[96:111]
	v_add_f32_e32 v76, v50, v116
	v_add_f32_e32 v76, v51, v76
	v_add_f32_e32 v76, v52, v76
	v_add_f32_e32 v76, v53, v76
	v_cvt_pk_bf16_f32 v124, v48, v49
	v_cvt_pk_bf16_f32 v125, v50, v51
	ds_read_b64_tr_b16 v[48:49], v181 offset:30720
	ds_read_b64_tr_b16 v[50:51], v181 offset:31232
	v_mfma_f32_32x32x16_bf16 v[80:95], v[152:155], v[120:123], v[80:95]
	v_add_f32_e32 v76, v54, v76
	v_add_f32_e32 v76, v55, v76
	v_add_f32_e32 v76, v56, v76
	v_add_f32_e32 v76, v57, v76
	v_cvt_pk_bf16_f32 v126, v52, v53
	v_cvt_pk_bf16_f32 v127, v54, v55
	ds_read_b64_tr_b16 v[52:53], v181 offset:27648
	ds_read_b64_tr_b16 v[54:55], v181 offset:28160
	v_mfma_f32_32x32x16_bf16 v[96:111], v[148:151], v[112:115], v[96:111]
	v_add_f32_e32 v76, v58, v76
	v_add_f32_e32 v76, v59, v76
	v_add_f32_e32 v76, v60, v76
	v_add_f32_e32 v76, v61, v76
	v_cvt_pk_bf16_f32 v116, v56, v57
	v_cvt_pk_bf16_f32 v117, v58, v59
	ds_read_b64_tr_b16 v[56:57], v181 offset:31744
	ds_read_b64_tr_b16 v[58:59], v181 offset:32256
	v_mfma_f32_32x32x16_bf16 v[80:95], v[144:147], v[112:115], v[80:95]
	v_add_f32_e32 v76, v62, v76
	v_add_f32_e32 v76, v63, v76
	v_cvt_pk_bf16_f32 v118, v60, v61
	v_cvt_pk_bf16_f32 v119, v62, v63
	v_max_f32_e32 v60, v96, v97
	s_nop 6
	v_max3_f32 v61, v98, v99, v81
	v_max3_f32 v60, v60, v80, v82
	v_max3_f32 v60, v60, v83, v100
	v_max3_f32 v61, v61, v102, v103
	v_max3_f32 v60, v60, v101, v84
	v_max3_f32 v61, v61, v86, v87
	v_max3_f32 v60, v60, v85, v104
	v_max3_f32 v61, v61, v106, v107
	v_max3_f32 v60, v60, v105, v88
	v_max3_f32 v61, v61, v90, v91
	v_max3_f32 v60, v60, v89, v108
	v_max3_f32 v61, v61, v110, v111
	v_max3_f32 v60, v60, v109, v92
	v_max3_f32 v61, v61, v94, v95
	v_max3_f32 v60, v60, v93, v61
	v_mov_b32_e32 v61, v60
	s_nop 1
	v_permlane32_swap_b32_e32 v60, v61
	v_max_f32_e32 v60, v60, v61
	v_cmp_lt_f32_e32 vcc, s29, v60
	s_cmp_lg_u64 vcc, 0
	v_add_f32_e32 v191, v192, v76
	s_cselect_b64 s[44:45], -1, 0
	s_cbranch_vccnz .LBB0_652

.LBB0_647:
	s_add_i32 s44, s68, 0x2000
	s_cmpk_lg_i32 s68, 0x4000
	s_cselect_b32 s60, s44, 0
	s_mov_b64 s[44:45], 0x1490a000
	v_lshl_add_u64 v[78:79], v[186:187], 0, s[44:45]
	s_add_i32 s44, s68, s35
	s_mov_b32 m0, s44
	s_nop 0
	global_load_lds_dwordx4 v[78:79], off
	s_mov_b64 s[44:45], 0x15206000
	v_lshl_add_u64 v[78:79], v[188:189], 0, s[44:45]
	s_add_i32 s44, s60, s49
	s_mov_b32 m0, s44
	s_nop 0
	global_load_lds_dwordx4 v[78:79], off
	v_add_u32_e32 v192, s70, v203
	ds_read_b64_tr_b16 v[148:149], v192 offset:24576
	ds_read_b64_tr_b16 v[150:151], v192 offset:25088
	v_mfma_f32_32x32x16_bf16 v[64:79], v[60:63], v[140:143], v[32:47]
	v_add_f32_e32 v48, v96, v97
	v_add_f32_e32 v48, v98, v48
	v_add_f32_e32 v48, v99, v48
	v_add_f32_e32 v48, v100, v48
	v_add_f32_e32 v48, v101, v48
	v_cvt_pk_bf16_f32 v136, v96, v97
	v_cvt_pk_bf16_f32 v137, v98, v99
	ds_read_b64_tr_b16 v[144:145], v192 offset:28672
	ds_read_b64_tr_b16 v[146:147], v192 offset:29184
	v_add_f32_e32 v48, v102, v48
	v_add_f32_e32 v48, v103, v48
	v_add_f32_e32 v48, v104, v48
	v_add_f32_e32 v116, v105, v48
	v_mfma_f32_32x32x16_bf16 v[48:63], v[172:175], v[140:143], v[32:47]
	v_cvt_pk_bf16_f32 v138, v100, v101
	v_cvt_pk_bf16_f32 v139, v102, v103
	ds_read_b64_tr_b16 v[96:97], v192 offset:25600
	ds_read_b64_tr_b16 v[98:99], v192 offset:26112
	v_mfma_f32_32x32x16_bf16 v[64:79], v[176:179], v[132:135], v[64:79]
	v_add_f32_e32 v100, v106, v116
	v_add_f32_e32 v100, v107, v100
	v_add_f32_e32 v100, v108, v100
	v_add_f32_e32 v116, v109, v100
	v_cvt_pk_bf16_f32 v128, v104, v105
	v_cvt_pk_bf16_f32 v129, v106, v107
	ds_read_b64_tr_b16 v[100:101], v192 offset:29696
	ds_read_b64_tr_b16 v[102:103], v192 offset:30208
	v_mfma_f32_32x32x16_bf16 v[48:63], v[168:171], v[132:135], v[48:63]
	v_add_f32_e32 v104, v110, v116
	v_add_f32_e32 v104, v111, v104
	v_add_f32_e32 v104, v80, v104
	v_add_f32_e32 v116, v81, v104
	v_cvt_pk_bf16_f32 v130, v108, v109
	v_cvt_pk_bf16_f32 v131, v110, v111
	ds_read_b64_tr_b16 v[104:105], v192 offset:26624
	ds_read_b64_tr_b16 v[106:107], v192 offset:27136
	v_mfma_f32_32x32x16_bf16 v[64:79], v[164:167], v[120:123], v[64:79]
	v_add_f32_e32 v108, v82, v116
	v_add_f32_e32 v108, v83, v108
	v_add_f32_e32 v108, v84, v108
	v_add_f32_e32 v108, v85, v108
	v_cvt_pk_bf16_f32 v124, v80, v81
	v_cvt_pk_bf16_f32 v125, v82, v83
	ds_read_b64_tr_b16 v[80:81], v192 offset:30720
	ds_read_b64_tr_b16 v[82:83], v192 offset:31232
	v_mfma_f32_32x32x16_bf16 v[48:63], v[160:163], v[120:123], v[48:63]
	v_add_f32_e32 v108, v86, v108
	v_add_f32_e32 v108, v87, v108
	v_add_f32_e32 v108, v88, v108
	v_add_f32_e32 v108, v89, v108
	v_cvt_pk_bf16_f32 v126, v84, v85
	v_cvt_pk_bf16_f32 v127, v86, v87
	ds_read_b64_tr_b16 v[84:85], v192 offset:27648
	ds_read_b64_tr_b16 v[86:87], v192 offset:28160
	v_mfma_f32_32x32x16_bf16 v[64:79], v[156:159], v[112:115], v[64:79]
	v_add_f32_e32 v108, v90, v108
	v_add_f32_e32 v108, v91, v108
	v_add_f32_e32 v108, v92, v108
	v_add_f32_e32 v108, v93, v108
	v_cvt_pk_bf16_f32 v116, v88, v89
	v_cvt_pk_bf16_f32 v117, v90, v91
	ds_read_b64_tr_b16 v[88:89], v192 offset:31744
	ds_read_b64_tr_b16 v[90:91], v192 offset:32256
	v_mfma_f32_32x32x16_bf16 v[48:63], v[152:155], v[112:115], v[48:63]
	v_add_f32_e32 v108, v94, v108
	v_add_f32_e32 v108, v95, v108
	v_cvt_pk_bf16_f32 v118, v92, v93
	v_cvt_pk_bf16_f32 v119, v94, v95
	v_max_f32_e32 v92, v64, v65
	s_nop 6
	v_max3_f32 v93, v66, v67, v49
	v_max3_f32 v92, v92, v48, v50
	v_max3_f32 v92, v92, v51, v68
	v_max3_f32 v93, v93, v70, v71
	v_max3_f32 v92, v92, v69, v52
	v_max3_f32 v93, v93, v54, v55
	v_max3_f32 v92, v92, v53, v72
	v_max3_f32 v93, v93, v74, v75
	v_max3_f32 v92, v92, v73, v56
	v_max3_f32 v93, v93, v58, v59
	v_max3_f32 v92, v92, v57, v76
	v_max3_f32 v93, v93, v78, v79
	v_max3_f32 v92, v92, v77, v60
	v_max3_f32 v93, v93, v62, v63
	v_max3_f32 v92, v92, v61, v93
	v_mov_b32_e32 v93, v92
	s_nop 1
	v_permlane32_swap_b32_e32 v92, v93
	v_max_f32_e32 v92, v92, v93
	v_cmp_lt_f32_e32 vcc, s29, v92
	s_cmp_lg_u64 vcc, 0
	v_add_f32_e32 v192, v191, v108
	s_cselect_b64 s[44:45], -1, 0
	s_cbranch_vccnz .LBB0_655

.LBB0_721:
	s_movk_i32 s42, 0xe000
	s_mov_b32 s43, -1
	v_lshl_add_u64 v[142:143], v[214:215], 0, s[42:43]
	s_add_i32 s42, s71, s49
	s_mov_b32 m0, s42
	s_nop 0
	global_load_lds_dwordx4 v[142:143], off
	s_movk_i32 s42, 0xbf80
	s_mov_b32 s43, -1
	v_lshl_add_u64 v[142:143], v[212:213], 0, s[42:43]
	s_lshl_b32 s42, s61, 1
	s_add_i32 s44, s42, s60
	s_mov_b32 m0, s44
	s_nop 0
	global_load_lds_dwordx4 v[142:143], off
	s_movk_i32 s42, 0xc000
	s_mov_b32 s43, -1
	v_lshl_add_u64 v[142:143], v[212:213], 0, s[42:43]
	s_add_i32 s42, s44, 0x2000
	s_mov_b32 m0, s42
	s_nop 0
	global_load_lds_dwordx4 v[142:143], off
	v_mfma_f32_32x32x16_bf16 v[128:143], v[204:207], v[172:175], v[64:79]
	v_add_f32_e32 v112, v96, v97
	v_add_f32_e32 v112, v98, v112
	v_add_f32_e32 v112, v99, v112
	v_add_f32_e32 v112, v100, v112
	v_add_f32_e32 v112, v101, v112
	v_cvt_pk_bf16_f32 v160, v96, v97
	v_cvt_pk_bf16_f32 v161, v98, v99
	v_add_f32_e32 v96, v102, v112
	v_mfma_f32_32x32x16_bf16 v[112:127], v[200:203], v[172:175], v[64:79]
	v_add_f32_e32 v96, v103, v96
	v_add_f32_e32 v96, v104, v96
	v_add_f32_e32 v96, v105, v96
	v_cvt_pk_bf16_f32 v162, v100, v101
	v_cvt_pk_bf16_f32 v163, v102, v103
	v_mfma_f32_32x32x16_bf16 v[128:143], v[196:199], v[168:171], v[128:143]
	v_add_f32_e32 v96, v106, v96
	v_add_f32_e32 v96, v107, v96
	v_add_f32_e32 v96, v108, v96
	v_add_f32_e32 v96, v109, v96
	v_cvt_pk_bf16_f32 v152, v104, v105
	v_cvt_pk_bf16_f32 v153, v106, v107
	v_mfma_f32_32x32x16_bf16 v[112:127], v[192:195], v[168:171], v[112:127]
	v_add_f32_e32 v96, v110, v96
	v_add_f32_e32 v96, v111, v96
	v_add_f32_e32 v96, v80, v96
	v_add_f32_e32 v96, v81, v96
	v_cvt_pk_bf16_f32 v154, v108, v109
	v_cvt_pk_bf16_f32 v155, v110, v111
	v_mfma_f32_32x32x16_bf16 v[128:143], v[188:191], v[164:167], v[128:143]
	v_add_f32_e32 v96, v82, v96
	v_add_f32_e32 v96, v83, v96
	v_add_f32_e32 v96, v84, v96
	v_add_f32_e32 v96, v85, v96
	v_cvt_pk_bf16_f32 v148, v80, v81
	v_cvt_pk_bf16_f32 v149, v82, v83
	v_mfma_f32_32x32x16_bf16 v[112:127], v[184:187], v[164:167], v[112:127]
	v_add_f32_e32 v80, v86, v96
	v_add_f32_e32 v80, v87, v80
	v_add_f32_e32 v80, v88, v80
	v_add_f32_e32 v80, v89, v80
	v_cvt_pk_bf16_f32 v150, v84, v85
	v_cvt_pk_bf16_f32 v151, v86, v87
	v_mfma_f32_32x32x16_bf16 v[128:143], v[180:183], v[156:159], v[128:143]
	v_add_f32_e32 v80, v90, v80
	v_add_f32_e32 v80, v91, v80
	v_add_f32_e32 v80, v92, v80
	v_add_f32_e32 v80, v93, v80
	v_cvt_pk_bf16_f32 v144, v88, v89
	v_cvt_pk_bf16_f32 v145, v90, v91
	v_mfma_f32_32x32x16_bf16 v[112:127], v[176:179], v[156:159], v[112:127]
	v_add_f32_e32 v80, v94, v80
	v_add_f32_e32 v82, v95, v80
	v_cvt_pk_bf16_f32 v146, v92, v93
	v_cvt_pk_bf16_f32 v147, v94, v95
	s_nop 0
	v_max_f32_e32 v80, v128, v129
	s_nop 5
	v_max3_f32 v81, v130, v131, v113
	v_max3_f32 v80, v80, v112, v114
	v_max3_f32 v80, v80, v115, v132
	v_max3_f32 v81, v81, v134, v135
	v_max3_f32 v80, v80, v133, v116
	v_max3_f32 v81, v81, v118, v119
	v_max3_f32 v80, v80, v117, v136
	v_max3_f32 v81, v81, v138, v139
	v_max3_f32 v80, v80, v137, v120
	v_max3_f32 v81, v81, v122, v123
	v_max3_f32 v80, v80, v121, v140
	v_max3_f32 v81, v81, v142, v143
	v_max3_f32 v80, v80, v141, v124
	v_max3_f32 v81, v81, v126, v127
	v_max3_f32 v80, v80, v125, v81
	v_mov_b32_e32 v81, v80
	s_nop 1
	v_permlane32_swap_b32_e32 v80, v81
	v_max_f32_e32 v80, v80, v81
	v_cmp_lt_f32_e32 vcc, s29, v80
	s_cmp_lg_u64 vcc, 0
	v_add_f32_e32 v204, v252, v82
	s_cselect_b64 s[42:43], -1, 0
	s_cbranch_vccnz .LBB0_729

.LBB0_724:
	s_add_i32 s42, s61, 0x2000
	s_cmpk_lg_i32 s61, 0x4000
	s_cselect_b32 s65, s42, 0
	s_add_i32 s42, s61, s49
	s_mov_b32 m0, s42
	s_nop 0
	global_load_lds_dwordx4 v[214:215], off
	s_movk_i32 s42, 0xff80
	s_mov_b32 s43, -1
	v_lshl_add_u64 v[110:111], v[212:213], 0, s[42:43]
	s_lshl_b32 s42, s65, 1
	s_add_i32 s42, s42, s60
	s_mov_b32 m0, s42
	s_nop 0
	global_load_lds_dwordx4 v[110:111], off
	s_addk_i32 s42, 0x2000
	s_mov_b32 m0, s42
	s_nop 0
	global_load_lds_dwordx4 v[212:213], off
	v_mfma_f32_32x32x16_bf16 v[96:111], v[80:83], v[172:175], v[64:79]
	v_add_f32_e32 v84, v128, v129
	v_add_f32_e32 v84, v130, v84
	v_add_f32_e32 v84, v131, v84
	v_add_f32_e32 v84, v132, v84
	v_add_f32_e32 v84, v133, v84
	v_cvt_pk_bf16_f32 v160, v128, v129
	v_cvt_pk_bf16_f32 v161, v130, v131
	v_add_f32_e32 v80, v134, v84
	v_add_f32_e32 v80, v135, v80
	v_add_f32_e32 v80, v136, v80
	v_add_f32_e32 v128, v137, v80
	v_mfma_f32_32x32x16_bf16 v[80:95], v[196:199], v[172:175], v[64:79]
	v_cvt_pk_bf16_f32 v162, v132, v133
	v_cvt_pk_bf16_f32 v163, v134, v135
	v_mfma_f32_32x32x16_bf16 v[96:111], v[200:203], v[168:171], v[96:111]
	v_add_f32_e32 v128, v138, v128
	v_add_f32_e32 v128, v139, v128
	v_add_f32_e32 v128, v140, v128
	v_add_f32_e32 v128, v141, v128
	v_cvt_pk_bf16_f32 v152, v136, v137
	v_cvt_pk_bf16_f32 v153, v138, v139
	v_mfma_f32_32x32x16_bf16 v[80:95], v[192:195], v[168:171], v[80:95]
	v_add_f32_e32 v128, v142, v128
	v_add_f32_e32 v128, v143, v128
	v_add_f32_e32 v128, v112, v128
	v_add_f32_e32 v128, v113, v128
	v_cvt_pk_bf16_f32 v154, v140, v141
	v_cvt_pk_bf16_f32 v155, v142, v143
	v_mfma_f32_32x32x16_bf16 v[96:111], v[188:191], v[164:167], v[96:111]
	v_add_f32_e32 v128, v114, v128
	v_add_f32_e32 v128, v115, v128
	v_add_f32_e32 v128, v116, v128
	v_add_f32_e32 v128, v117, v128
	v_cvt_pk_bf16_f32 v148, v112, v113
	v_cvt_pk_bf16_f32 v149, v114, v115
	v_mfma_f32_32x32x16_bf16 v[80:95], v[184:187], v[164:167], v[80:95]
	v_add_f32_e32 v112, v118, v128
	v_add_f32_e32 v112, v119, v112
	v_add_f32_e32 v112, v120, v112
	v_add_f32_e32 v112, v121, v112
	v_cvt_pk_bf16_f32 v150, v116, v117
	v_cvt_pk_bf16_f32 v151, v118, v119
	v_mfma_f32_32x32x16_bf16 v[96:111], v[180:183], v[156:159], v[96:111]
	v_add_f32_e32 v112, v122, v112
	v_add_f32_e32 v112, v123, v112
	v_add_f32_e32 v112, v124, v112
	v_add_f32_e32 v112, v125, v112
	v_cvt_pk_bf16_f32 v144, v120, v121
	v_cvt_pk_bf16_f32 v145, v122, v123
	v_mfma_f32_32x32x16_bf16 v[80:95], v[176:179], v[156:159], v[80:95]
	v_add_f32_e32 v112, v126, v112
	v_add_f32_e32 v114, v127, v112
	v_cvt_pk_bf16_f32 v146, v124, v125
	v_cvt_pk_bf16_f32 v147, v126, v127
	s_nop 0
	v_max_f32_e32 v112, v96, v97
	s_nop 5
	v_max3_f32 v113, v98, v99, v81
	v_max3_f32 v112, v112, v80, v82
	v_max3_f32 v112, v112, v83, v100
	v_max3_f32 v113, v113, v102, v103
	v_max3_f32 v112, v112, v101, v84
	v_max3_f32 v113, v113, v86, v87
	v_max3_f32 v112, v112, v85, v104
	v_max3_f32 v113, v113, v106, v107
	v_max3_f32 v112, v112, v105, v88
	v_max3_f32 v113, v113, v90, v91
	v_max3_f32 v112, v112, v89, v108
	v_max3_f32 v113, v113, v110, v111
	v_max3_f32 v112, v112, v109, v92
	v_max3_f32 v113, v113, v94, v95
	v_max3_f32 v112, v112, v93, v113
	v_mov_b32_e32 v113, v112
	s_nop 1
	v_permlane32_swap_b32_e32 v112, v113
	v_max_f32_e32 v112, v112, v113
	v_cmp_lt_f32_e32 vcc, s29, v112
	s_cmp_lg_u64 vcc, 0
	v_add_f32_e32 v252, v204, v114
	s_cselect_b64 s[42:43], -1, 0
	s_cbranch_vccnz .LBB0_732
